# GEMM K-loops: merged waits, m0 from ldsw+literal, R3 LDS read bases hoisted (no VALU left in load-role segments of P1/P3/P4)
# speedup vs baseline: 1.0076x; 1.0019x over previous
.LBB0_175:
	s_mov_b32 s28, s29
	s_ashr_i32 s29, s29, 31
	s_lshl_b64 s[34:35], s[28:29], 20
	s_add_u32 s34, s90, s34
	s_addc_u32 s35, s91, s35
	s_and_b64 s[36:37], s[30:31], exec
	s_mov_b32 s26, s27
	s_cselect_b32 s2, s35, s43
	s_cselect_b32 s29, s34, s42
	s_ashr_i32 s27, s27, 31
	s_lshl_b64 s[36:37], s[26:27], 20
	s_add_u32 s36, s92, s36
	s_addc_u32 s37, s93, s37
	s_and_b64 s[44:45], s[30:31], exec
	s_cselect_b32 s27, s37, s41
	s_cselect_b32 s39, s36, s40
	s_add_u32 s46, s40, 0x100
	s_addc_u32 s47, s41, 0
	s_add_u32 s40, s42, 0x80080
	v_mov_b32_e32 v2, 0
	s_addc_u32 s41, s43, 0
	s_mov_b32 s52, -2
	v_mov_b32_e32 v3, v2
	v_mov_b32_e32 v4, v2
	v_mov_b32_e32 v5, v2
	v_mov_b32_e32 v6, v2
	v_mov_b32_e32 v7, v2
	v_mov_b32_e32 v8, v2
	v_mov_b32_e32 v9, v2
	s_waitcnt vmcnt(0)
	v_mov_b32_e32 v18, v2
	v_mov_b32_e32 v19, v2
	v_mov_b32_e32 v20, v2
	v_mov_b32_e32 v21, v2
	v_mov_b32_e32 v22, v2
	v_mov_b32_e32 v23, v2
	v_mov_b32_e32 v24, v2
	v_mov_b32_e32 v25, v2
	v_mov_b32_e32 v34, v2
	v_mov_b32_e32 v35, v2
	v_mov_b32_e32 v36, v2
	v_mov_b32_e32 v37, v2
	v_mov_b32_e32 v38, v2
	v_mov_b32_e32 v39, v2
	v_mov_b32_e32 v40, v2
	v_mov_b32_e32 v41, v2
	v_mov_b32_e32 v50, v2
	v_mov_b32_e32 v51, v2
	v_mov_b32_e32 v52, v2
	v_mov_b32_e32 v53, v2
	v_mov_b32_e32 v54, v2
	v_mov_b32_e32 v55, v2
	v_mov_b32_e32 v56, v2
	v_mov_b32_e32 v57, v2
	v_mov_b32_e32 v10, v2
	v_mov_b32_e32 v11, v2
	v_mov_b32_e32 v12, v2
	v_mov_b32_e32 v13, v2
	v_mov_b32_e32 v14, v2
	v_mov_b32_e32 v15, v2
	v_mov_b32_e32 v16, v2
	v_mov_b32_e32 v17, v2
	v_mov_b32_e32 v26, v2
	v_mov_b32_e32 v27, v2
	v_mov_b32_e32 v28, v2
	v_mov_b32_e32 v29, v2
	v_mov_b32_e32 v30, v2
	v_mov_b32_e32 v31, v2
	v_mov_b32_e32 v32, v2
	v_mov_b32_e32 v33, v2
	v_mov_b32_e32 v42, v2
	v_mov_b32_e32 v43, v2
	v_mov_b32_e32 v44, v2
	v_mov_b32_e32 v45, v2
	v_mov_b32_e32 v46, v2
	v_mov_b32_e32 v47, v2
	v_mov_b32_e32 v48, v2
	v_mov_b32_e32 v49, v2
	v_mov_b32_e32 v66, v2
	v_mov_b32_e32 v67, v2
	v_mov_b32_e32 v68, v2
	v_mov_b32_e32 v69, v2
	v_mov_b32_e32 v70, v2
	v_mov_b32_e32 v71, v2
	v_mov_b32_e32 v72, v2
	v_mov_b32_e32 v73, v2
	v_mov_b32_e32 v74, v2
	v_mov_b32_e32 v75, v2
	v_mov_b32_e32 v76, v2
	v_mov_b32_e32 v77, v2
	v_mov_b32_e32 v86, v2
	v_mov_b32_e32 v87, v2
	v_mov_b32_e32 v88, v2
	v_mov_b32_e32 v89, v2
	v_mov_b32_e32 v98, v2
	v_mov_b32_e32 v99, v2
	v_mov_b32_e32 v100, v2
	v_mov_b32_e32 v101, v2
	v_mov_b32_e32 v110, v2
	v_mov_b32_e32 v111, v2
	v_mov_b32_e32 v112, v2
	v_mov_b32_e32 v113, v2
	v_mov_b32_e32 v130, v2
	v_mov_b32_e32 v131, v2
	v_mov_b32_e32 v132, v2
	v_mov_b32_e32 v133, v2
	v_mov_b32_e32 v134, v2
	v_mov_b32_e32 v135, v2
	v_mov_b32_e32 v136, v2
	v_mov_b32_e32 v137, v2
	v_mov_b32_e32 v154, v2
	v_mov_b32_e32 v155, v2
	v_mov_b32_e32 v156, v2
	v_mov_b32_e32 v157, v2
	v_mov_b32_e32 v158, v2
	v_mov_b32_e32 v159, v2
	v_mov_b32_e32 v160, v2
	v_mov_b32_e32 v161, v2
	v_mov_b32_e32 v90, v2
	v_mov_b32_e32 v91, v2
	v_mov_b32_e32 v92, v2
	v_mov_b32_e32 v93, v2
	v_mov_b32_e32 v94, v2
	v_mov_b32_e32 v95, v2
	v_mov_b32_e32 v96, v2
	v_mov_b32_e32 v97, v2
	v_mov_b32_e32 v114, v2
	v_mov_b32_e32 v115, v2
	v_mov_b32_e32 v116, v2
	v_mov_b32_e32 v117, v2
	v_mov_b32_e32 v118, v2
	v_mov_b32_e32 v119, v2
	v_mov_b32_e32 v120, v2
	v_mov_b32_e32 v121, v2
	v_mov_b32_e32 v138, v2
	v_mov_b32_e32 v139, v2
	v_mov_b32_e32 v140, v2
	v_mov_b32_e32 v141, v2
	v_mov_b32_e32 v142, v2
	v_mov_b32_e32 v143, v2
	v_mov_b32_e32 v144, v2
	v_mov_b32_e32 v145, v2
	v_mov_b32_e32 v162, v2
	v_mov_b32_e32 v163, v2
	v_mov_b32_e32 v164, v2
	v_mov_b32_e32 v165, v2
	v_mov_b32_e32 v166, v2
	v_mov_b32_e32 v167, v2
	v_mov_b32_e32 v168, v2
	v_mov_b32_e32 v169, v2
	v_add_u32_e32 v212, 0x18000, v218
	v_add_u32_e32 v213, 0x1c000, v218
.LBB0_176:
	ds_read_b128 v[58:61], v219
	ds_read_b128 v[62:65], v219 offset:1024
	ds_read_b128 v[78:81], v219 offset:2048
	ds_read_b128 v[82:85], v219 offset:3072
	ds_read_b128 v[102:105], v220
	ds_read_b128 v[106:109], v220 offset:1024
	ds_read_b128 v[122:125], v220 offset:2048
	ds_read_b128 v[126:129], v220 offset:3072
	s_add_u32 s42, s40, 0xfff80080
	s_addc_u32 s43, s41, -1
	s_cmp_eq_u32 s52, 28
	s_cselect_b32 s45, s2, s43
	s_cselect_b32 s44, s29, s42
	s_cselect_b32 s43, s27, s47
	s_cselect_b32 s42, s39, s46
	s_add_i32 m0, s49, 0xc000
	ds_read_b128 v[146:149], v221
	ds_read_b128 v[150:153], v221 offset:1024
	ds_read_b128 v[170:173], v221 offset:2048
	ds_read_b128 v[174:177], v221 offset:3072
	ds_read_b128 v[178:181], v221 offset:4096
	ds_read_b128 v[182:185], v221 offset:5120
	ds_read_b128 v[186:189], v221 offset:6144
	ds_read_b128 v[190:193], v221 offset:7168
	global_load_lds_dwordx4 v206, s[40:41]
	s_add_i32 m0, s49, 0xe000
	s_nop 0
	global_load_lds_dwordx4 v208, s[40:41]
	s_waitcnt vmcnt(8) lgkmcnt(0)
	s_barrier
	v_mfma_f32_16x16x32_bf16 v[166:169], v[58:61], v[146:149], v[166:169]
	v_mfma_f32_16x16x32_bf16 v[162:165], v[78:81], v[146:149], v[162:165]
	v_mfma_f32_16x16x32_bf16 v[142:145], v[58:61], v[170:173], v[142:145]
	v_mfma_f32_16x16x32_bf16 v[138:141], v[78:81], v[170:173], v[138:141]
	v_mfma_f32_16x16x32_bf16 v[118:121], v[58:61], v[178:181], v[118:121]
	v_mfma_f32_16x16x32_bf16 v[114:117], v[78:81], v[178:181], v[114:117]
	v_mfma_f32_16x16x32_bf16 v[94:97], v[58:61], v[186:189], v[94:97]
	v_mfma_f32_16x16x32_bf16 v[90:93], v[78:81], v[186:189], v[90:93]
	v_mfma_f32_16x16x32_bf16 v[166:169], v[62:65], v[150:153], v[166:169]
	v_mfma_f32_16x16x32_bf16 v[162:165], v[82:85], v[150:153], v[162:165]
	v_mfma_f32_16x16x32_bf16 v[142:145], v[62:65], v[174:177], v[142:145]
	v_mfma_f32_16x16x32_bf16 v[138:141], v[82:85], v[174:177], v[138:141]
	v_mfma_f32_16x16x32_bf16 v[118:121], v[62:65], v[182:185], v[118:121]
	v_mfma_f32_16x16x32_bf16 v[114:117], v[82:85], v[182:185], v[114:117]
	v_mfma_f32_16x16x32_bf16 v[94:97], v[62:65], v[190:193], v[94:97]
	v_mfma_f32_16x16x32_bf16 v[90:93], v[82:85], v[190:193], v[90:93]
	v_mfma_f32_16x16x32_bf16 v[158:161], v[102:105], v[146:149], v[158:161]
	v_mfma_f32_16x16x32_bf16 v[134:137], v[102:105], v[170:173], v[134:137]
	v_mfma_f32_16x16x32_bf16 v[130:133], v[122:125], v[170:173], v[130:133]
	v_mfma_f32_16x16x32_bf16 v[110:113], v[102:105], v[178:181], v[110:113]
	v_mfma_f32_16x16x32_bf16 v[98:101], v[122:125], v[178:181], v[98:101]
	v_mfma_f32_16x16x32_bf16 v[86:89], v[102:105], v[186:189], v[86:89]
	v_mfma_f32_16x16x32_bf16 v[74:77], v[122:125], v[186:189], v[74:77]
	v_mfma_f32_16x16x32_bf16 v[158:161], v[106:109], v[150:153], v[158:161]
	v_mfma_f32_16x16x32_bf16 v[146:149], v[122:125], v[146:149], v[154:157]
	v_mfma_f32_16x16x32_bf16 v[134:137], v[106:109], v[174:177], v[134:137]
	v_mfma_f32_16x16x32_bf16 v[130:133], v[126:129], v[174:177], v[130:133]
	v_mfma_f32_16x16x32_bf16 v[110:113], v[106:109], v[182:185], v[110:113]
	v_mfma_f32_16x16x32_bf16 v[98:101], v[126:129], v[182:185], v[98:101]
	v_mfma_f32_16x16x32_bf16 v[86:89], v[106:109], v[190:193], v[86:89]
	v_mfma_f32_16x16x32_bf16 v[74:77], v[126:129], v[190:193], v[74:77]
	v_mfma_f32_16x16x32_bf16 v[146:149], v[126:129], v[150:153], v[146:149]
	s_barrier
	s_add_i32 m0, s48, 0x10000
	ds_read_b128 v[150:153], v221 offset:16384
	ds_read_b128 v[154:157], v221 offset:17408
	ds_read_b128 v[170:173], v221 offset:18432
	ds_read_b128 v[174:177], v221 offset:19456
	ds_read_b128 v[178:181], v221 offset:20480
	ds_read_b128 v[182:185], v221 offset:21504
	ds_read_b128 v[186:189], v221 offset:22528
	ds_read_b128 v[190:193], v221 offset:23552
	global_load_lds_dwordx4 v198, s[42:43]
	s_add_i32 m0, s48, 0x12000
	s_add_u32 s54, s42, 0x80000
	s_addc_u32 s55, s43, 0
	global_load_lds_dwordx4 v202, s[42:43]
	s_add_i32 m0, s48, 0x14000
	s_nop 0
	global_load_lds_dwordx4 v198, s[54:55]
	s_add_i32 m0, s48, 0x16000
	s_nop 0
	global_load_lds_dwordx4 v202, s[54:55]
	s_mov_b32 m0, s49
	s_nop 0
	global_load_lds_dwordx4 v196, s[44:45]
	s_mov_b32 m0, s50
	s_nop 0
	global_load_lds_dwordx4 v200, s[44:45]
	s_waitcnt vmcnt(8) lgkmcnt(0)
	s_barrier
	v_mfma_f32_16x16x32_bf16 v[70:73], v[58:61], v[150:153], v[70:73]
	v_mfma_f32_16x16x32_bf16 v[66:69], v[78:81], v[150:153], v[66:69]
	v_mfma_f32_16x16x32_bf16 v[46:49], v[58:61], v[170:173], v[46:49]
	v_mfma_f32_16x16x32_bf16 v[42:45], v[78:81], v[170:173], v[42:45]
	v_mfma_f32_16x16x32_bf16 v[30:33], v[58:61], v[178:181], v[30:33]
	v_mfma_f32_16x16x32_bf16 v[26:29], v[78:81], v[178:181], v[26:29]
	v_mfma_f32_16x16x32_bf16 v[14:17], v[58:61], v[186:189], v[14:17]
	v_mfma_f32_16x16x32_bf16 v[10:13], v[78:81], v[186:189], v[10:13]
	v_mfma_f32_16x16x32_bf16 v[70:73], v[62:65], v[154:157], v[70:73]
	v_mfma_f32_16x16x32_bf16 v[66:69], v[82:85], v[154:157], v[66:69]
	v_mfma_f32_16x16x32_bf16 v[46:49], v[62:65], v[174:177], v[46:49]
	v_mfma_f32_16x16x32_bf16 v[42:45], v[82:85], v[174:177], v[42:45]
	v_mfma_f32_16x16x32_bf16 v[30:33], v[62:65], v[182:185], v[30:33]
	v_mfma_f32_16x16x32_bf16 v[26:29], v[82:85], v[182:185], v[26:29]
	v_mfma_f32_16x16x32_bf16 v[14:17], v[62:65], v[190:193], v[14:17]
	v_mfma_f32_16x16x32_bf16 v[10:13], v[82:85], v[190:193], v[10:13]
	v_mfma_f32_16x16x32_bf16 v[54:57], v[102:105], v[150:153], v[54:57]
	v_mfma_f32_16x16x32_bf16 v[50:53], v[122:125], v[150:153], v[50:53]
	v_mfma_f32_16x16x32_bf16 v[38:41], v[102:105], v[170:173], v[38:41]
	v_mfma_f32_16x16x32_bf16 v[34:37], v[122:125], v[170:173], v[34:37]
	v_mfma_f32_16x16x32_bf16 v[22:25], v[102:105], v[178:181], v[22:25]
	v_mfma_f32_16x16x32_bf16 v[18:21], v[122:125], v[178:181], v[18:21]
	v_mfma_f32_16x16x32_bf16 v[6:9], v[102:105], v[186:189], v[6:9]
	v_mfma_f32_16x16x32_bf16 v[2:5], v[122:125], v[186:189], v[2:5]
	v_mfma_f32_16x16x32_bf16 v[54:57], v[106:109], v[154:157], v[54:57]
	v_mfma_f32_16x16x32_bf16 v[50:53], v[126:129], v[154:157], v[50:53]
	v_mfma_f32_16x16x32_bf16 v[38:41], v[106:109], v[174:177], v[38:41]
	v_mfma_f32_16x16x32_bf16 v[34:37], v[126:129], v[174:177], v[34:37]
	v_mfma_f32_16x16x32_bf16 v[22:25], v[106:109], v[182:185], v[22:25]
	v_mfma_f32_16x16x32_bf16 v[18:21], v[126:129], v[182:185], v[18:21]
	v_mfma_f32_16x16x32_bf16 v[6:9], v[106:109], v[190:193], v[6:9]
	v_mfma_f32_16x16x32_bf16 v[2:5], v[126:129], v[190:193], v[2:5]
	s_barrier
	ds_read_b128 v[58:61], v212
	ds_read_b128 v[62:65], v212 offset:1024
	ds_read_b128 v[78:81], v212 offset:2048
	ds_read_b128 v[82:85], v212 offset:3072
	ds_read_b128 v[102:105], v213
	ds_read_b128 v[106:109], v213 offset:1024
	ds_read_b128 v[122:125], v213 offset:2048
	ds_read_b128 v[126:129], v213 offset:3072
	s_add_u32 s44, s44, 0x80000
	s_addc_u32 s45, s45, 0
	s_mov_b32 m0, s51
	ds_read_b128 v[150:153], v221 offset:32768
	ds_read_b128 v[154:157], v221 offset:33792
	ds_read_b128 v[170:173], v221 offset:34816
	ds_read_b128 v[174:177], v221 offset:35840
	ds_read_b128 v[178:181], v221 offset:36864
	ds_read_b128 v[182:185], v221 offset:37888
	ds_read_b128 v[186:189], v221 offset:38912
	ds_read_b128 v[190:193], v221 offset:39936
	global_load_lds_dwordx4 v196, s[44:45]
	s_mov_b32 m0, s72
	s_nop 0
	global_load_lds_dwordx4 v200, s[44:45]
	s_waitcnt vmcnt(8) lgkmcnt(0)
	s_barrier
	v_mfma_f32_16x16x32_bf16 v[166:169], v[58:61], v[150:153], v[166:169]
	v_mfma_f32_16x16x32_bf16 v[162:165], v[78:81], v[150:153], v[162:165]
	v_mfma_f32_16x16x32_bf16 v[142:145], v[58:61], v[170:173], v[142:145]
	v_mfma_f32_16x16x32_bf16 v[138:141], v[78:81], v[170:173], v[138:141]
	v_mfma_f32_16x16x32_bf16 v[118:121], v[58:61], v[178:181], v[118:121]
	v_mfma_f32_16x16x32_bf16 v[114:117], v[78:81], v[178:181], v[114:117]
	v_mfma_f32_16x16x32_bf16 v[94:97], v[58:61], v[186:189], v[94:97]
	v_mfma_f32_16x16x32_bf16 v[90:93], v[78:81], v[186:189], v[90:93]
	v_mfma_f32_16x16x32_bf16 v[166:169], v[62:65], v[154:157], v[166:169]
	v_mfma_f32_16x16x32_bf16 v[162:165], v[82:85], v[154:157], v[162:165]
	v_mfma_f32_16x16x32_bf16 v[142:145], v[62:65], v[174:177], v[142:145]
	v_mfma_f32_16x16x32_bf16 v[138:141], v[82:85], v[174:177], v[138:141]
	v_mfma_f32_16x16x32_bf16 v[118:121], v[62:65], v[182:185], v[118:121]
	v_mfma_f32_16x16x32_bf16 v[114:117], v[82:85], v[182:185], v[114:117]
	v_mfma_f32_16x16x32_bf16 v[94:97], v[62:65], v[190:193], v[94:97]
	v_mfma_f32_16x16x32_bf16 v[90:93], v[82:85], v[190:193], v[90:93]
	v_mfma_f32_16x16x32_bf16 v[158:161], v[102:105], v[150:153], v[158:161]
	v_mfma_f32_16x16x32_bf16 v[146:149], v[122:125], v[150:153], v[146:149]
	v_mfma_f32_16x16x32_bf16 v[134:137], v[102:105], v[170:173], v[134:137]
	v_mfma_f32_16x16x32_bf16 v[130:133], v[122:125], v[170:173], v[130:133]
	v_mfma_f32_16x16x32_bf16 v[110:113], v[102:105], v[178:181], v[110:113]
	v_mfma_f32_16x16x32_bf16 v[98:101], v[122:125], v[178:181], v[98:101]
	v_mfma_f32_16x16x32_bf16 v[86:89], v[102:105], v[186:189], v[86:89]
	v_mfma_f32_16x16x32_bf16 v[74:77], v[122:125], v[186:189], v[74:77]
	v_mfma_f32_16x16x32_bf16 v[158:161], v[106:109], v[154:157], v[158:161]
	v_mfma_f32_16x16x32_bf16 v[154:157], v[126:129], v[154:157], v[146:149]
	v_mfma_f32_16x16x32_bf16 v[134:137], v[106:109], v[174:177], v[134:137]
	v_mfma_f32_16x16x32_bf16 v[130:133], v[126:129], v[174:177], v[130:133]
	v_mfma_f32_16x16x32_bf16 v[110:113], v[106:109], v[182:185], v[110:113]
	v_mfma_f32_16x16x32_bf16 v[98:101], v[126:129], v[182:185], v[98:101]
	v_mfma_f32_16x16x32_bf16 v[86:89], v[106:109], v[190:193], v[86:89]
	v_mfma_f32_16x16x32_bf16 v[74:77], v[126:129], v[190:193], v[74:77]
	s_barrier
	s_add_u32 s98, s44, 0xfff80080
	s_addc_u32 s99, s45, -1
	s_add_i32 m0, s48, 0x18000
	ds_read_b128 v[146:149], v221 offset:49152
	ds_read_b128 v[150:153], v221 offset:50176
	ds_read_b128 v[170:173], v221 offset:51200
	ds_read_b128 v[174:177], v221 offset:52224
	ds_read_b128 v[178:181], v221 offset:53248
	ds_read_b128 v[182:185], v221 offset:54272
	ds_read_b128 v[186:189], v221 offset:55296
	ds_read_b128 v[190:193], v221 offset:56320
	s_add_u32 s100, s42, 0x80
	s_addc_u32 s101, s43, 0
	global_load_lds_dwordx4 v198, s[100:101]
	s_add_i32 m0, s48, 0x1a000
	s_add_u32 s42, s42, 0x80080
	s_addc_u32 s43, s43, 0
	global_load_lds_dwordx4 v202, s[100:101]
	s_add_i32 m0, s48, 0x1c000
	s_nop 0
	global_load_lds_dwordx4 v198, s[42:43]
	s_add_i32 m0, s48, 0x1e000
	s_nop 0
	global_load_lds_dwordx4 v202, s[42:43]
	s_mov_b32 m0, s79
	s_nop 0
	global_load_lds_dwordx4 v196, s[98:99]
	s_mov_b32 m0, s80
	s_nop 0
	global_load_lds_dwordx4 v200, s[98:99]
	s_waitcnt vmcnt(8) lgkmcnt(0)
	s_barrier
	v_mfma_f32_16x16x32_bf16 v[70:73], v[58:61], v[146:149], v[70:73]
	v_mfma_f32_16x16x32_bf16 v[66:69], v[78:81], v[146:149], v[66:69]
	v_mfma_f32_16x16x32_bf16 v[46:49], v[58:61], v[170:173], v[46:49]
	v_mfma_f32_16x16x32_bf16 v[42:45], v[78:81], v[170:173], v[42:45]
	v_mfma_f32_16x16x32_bf16 v[30:33], v[58:61], v[178:181], v[30:33]
	v_mfma_f32_16x16x32_bf16 v[26:29], v[78:81], v[178:181], v[26:29]
	v_mfma_f32_16x16x32_bf16 v[14:17], v[58:61], v[186:189], v[14:17]
	v_mfma_f32_16x16x32_bf16 v[10:13], v[78:81], v[186:189], v[10:13]
	v_mfma_f32_16x16x32_bf16 v[70:73], v[62:65], v[150:153], v[70:73]
	v_mfma_f32_16x16x32_bf16 v[66:69], v[82:85], v[150:153], v[66:69]
	v_mfma_f32_16x16x32_bf16 v[46:49], v[62:65], v[174:177], v[46:49]
	v_mfma_f32_16x16x32_bf16 v[42:45], v[82:85], v[174:177], v[42:45]
	v_mfma_f32_16x16x32_bf16 v[30:33], v[62:65], v[182:185], v[30:33]
	v_mfma_f32_16x16x32_bf16 v[26:29], v[82:85], v[182:185], v[26:29]
	v_mfma_f32_16x16x32_bf16 v[14:17], v[62:65], v[190:193], v[14:17]
	v_mfma_f32_16x16x32_bf16 v[10:13], v[82:85], v[190:193], v[10:13]
	v_mfma_f32_16x16x32_bf16 v[54:57], v[102:105], v[146:149], v[54:57]
	v_mfma_f32_16x16x32_bf16 v[50:53], v[122:125], v[146:149], v[50:53]
	v_mfma_f32_16x16x32_bf16 v[38:41], v[102:105], v[170:173], v[38:41]
	v_mfma_f32_16x16x32_bf16 v[34:37], v[122:125], v[170:173], v[34:37]
	v_mfma_f32_16x16x32_bf16 v[22:25], v[102:105], v[178:181], v[22:25]
	v_mfma_f32_16x16x32_bf16 v[18:21], v[122:125], v[178:181], v[18:21]
	v_mfma_f32_16x16x32_bf16 v[6:9], v[102:105], v[186:189], v[6:9]
	v_mfma_f32_16x16x32_bf16 v[2:5], v[122:125], v[186:189], v[2:5]
	v_mfma_f32_16x16x32_bf16 v[54:57], v[106:109], v[150:153], v[54:57]
	v_mfma_f32_16x16x32_bf16 v[50:53], v[126:129], v[150:153], v[50:53]
	v_mfma_f32_16x16x32_bf16 v[38:41], v[106:109], v[174:177], v[38:41]
	v_mfma_f32_16x16x32_bf16 v[34:37], v[126:129], v[174:177], v[34:37]
	v_mfma_f32_16x16x32_bf16 v[22:25], v[106:109], v[182:185], v[22:25]
	v_mfma_f32_16x16x32_bf16 v[18:21], v[126:129], v[182:185], v[18:21]
	v_mfma_f32_16x16x32_bf16 v[6:9], v[106:109], v[190:193], v[6:9]
	v_mfma_f32_16x16x32_bf16 v[2:5], v[126:129], v[190:193], v[2:5]
	s_barrier
	s_add_i32 s52, s52, 2
	s_add_u32 s46, s46, 0x100
	s_addc_u32 s47, s47, 0
	s_add_u32 s40, s40, 0x100
	s_addc_u32 s41, s41, 0
	s_cmp_gt_u32 s52, 29
	s_cbranch_scc0 .LBB0_176
	s_and_b64 vcc, exec, s[24:25]
	s_cbranch_vccz .LBB0_179
	s_barrier

.LBB0_650:
	s_ashr_i32 s15, s14, 31
	s_lshl_b64 s[18:19], s[14:15], 20
	s_add_u32 s18, s92, s18
	s_addc_u32 s19, s93, s19
	s_and_b64 s[20:21], s[16:17], exec
	s_cselect_b32 s15, s19, s29
	s_cselect_b32 s23, s18, s28
	s_ashr_i32 s13, s12, 31
	s_lshl_b64 s[20:21], s[12:13], 20
	s_add_u32 s20, s94, s20
	s_addc_u32 s21, s95, s21
	s_and_b64 s[30:31], s[16:17], exec
	s_cselect_b32 s13, s21, s27
	s_cselect_b32 s43, s20, s26
	s_add_u32 s44, s26, 0x100
	s_addc_u32 s45, s27, 0
	s_add_u32 s26, s28, 0x80080
	v_mov_b32_e32 v2, 0
	s_addc_u32 s27, s29, 0
	s_mov_b32 s46, -2
	s_waitcnt lgkmcnt(0)
	v_mov_b32_e32 v3, v2
	v_mov_b32_e32 v4, v2
	v_mov_b32_e32 v5, v2
	v_mov_b32_e32 v6, v2
	v_mov_b32_e32 v7, v2
	v_mov_b32_e32 v8, v2
	v_mov_b32_e32 v9, v2
	v_mov_b32_e32 v18, v2
	v_mov_b32_e32 v19, v2
	v_mov_b32_e32 v20, v2
	v_mov_b32_e32 v21, v2
	v_mov_b32_e32 v22, v2
	v_mov_b32_e32 v23, v2
	v_mov_b32_e32 v24, v2
	v_mov_b32_e32 v25, v2
	v_mov_b32_e32 v34, v2
	v_mov_b32_e32 v35, v2
	v_mov_b32_e32 v36, v2
	v_mov_b32_e32 v37, v2
	v_mov_b32_e32 v38, v2
	v_mov_b32_e32 v39, v2
	v_mov_b32_e32 v40, v2
	v_mov_b32_e32 v41, v2
	v_mov_b32_e32 v50, v2
	v_mov_b32_e32 v51, v2
	v_mov_b32_e32 v52, v2
	v_mov_b32_e32 v53, v2
	v_mov_b32_e32 v54, v2
	v_mov_b32_e32 v55, v2
	v_mov_b32_e32 v56, v2
	v_mov_b32_e32 v57, v2
	v_mov_b32_e32 v10, v2
	v_mov_b32_e32 v11, v2
	v_mov_b32_e32 v12, v2
	v_mov_b32_e32 v13, v2
	v_mov_b32_e32 v14, v2
	v_mov_b32_e32 v15, v2
	v_mov_b32_e32 v16, v2
	v_mov_b32_e32 v17, v2
	v_mov_b32_e32 v26, v2
	v_mov_b32_e32 v27, v2
	v_mov_b32_e32 v28, v2
	v_mov_b32_e32 v29, v2
	v_mov_b32_e32 v30, v2
	v_mov_b32_e32 v31, v2
	v_mov_b32_e32 v32, v2
	v_mov_b32_e32 v33, v2
	v_mov_b32_e32 v42, v2
	v_mov_b32_e32 v43, v2
	v_mov_b32_e32 v44, v2
	v_mov_b32_e32 v45, v2
	v_mov_b32_e32 v46, v2
	v_mov_b32_e32 v47, v2
	v_mov_b32_e32 v48, v2
	v_mov_b32_e32 v49, v2
	v_mov_b32_e32 v58, v2
	v_mov_b32_e32 v59, v2
	v_mov_b32_e32 v60, v2
	v_mov_b32_e32 v61, v2
	v_mov_b32_e32 v62, v2
	v_mov_b32_e32 v63, v2
	v_mov_b32_e32 v64, v2
	v_mov_b32_e32 v65, v2
	v_mov_b32_e32 v66, v2
	v_mov_b32_e32 v67, v2
	v_mov_b32_e32 v68, v2
	v_mov_b32_e32 v69, v2
	v_mov_b32_e32 v70, v2
	v_mov_b32_e32 v71, v2
	v_mov_b32_e32 v72, v2
	v_mov_b32_e32 v73, v2
	v_mov_b32_e32 v82, v2
	v_mov_b32_e32 v83, v2
	v_mov_b32_e32 v84, v2
	v_mov_b32_e32 v85, v2
	v_mov_b32_e32 v86, v2
	v_mov_b32_e32 v87, v2
	v_mov_b32_e32 v88, v2
	v_mov_b32_e32 v89, v2
	v_mov_b32_e32 v98, v2
	v_mov_b32_e32 v99, v2
	v_mov_b32_e32 v100, v2
	v_mov_b32_e32 v101, v2
	v_mov_b32_e32 v102, v2
	v_mov_b32_e32 v103, v2
	v_mov_b32_e32 v104, v2
	v_mov_b32_e32 v105, v2
	v_mov_b32_e32 v114, v2
	v_mov_b32_e32 v115, v2
	v_mov_b32_e32 v116, v2
	v_mov_b32_e32 v117, v2
	v_mov_b32_e32 v118, v2
	v_mov_b32_e32 v119, v2
	v_mov_b32_e32 v120, v2
	v_mov_b32_e32 v121, v2
	v_mov_b32_e32 v74, v2
	v_mov_b32_e32 v75, v2
	v_mov_b32_e32 v76, v2
	v_mov_b32_e32 v77, v2
	v_mov_b32_e32 v78, v2
	v_mov_b32_e32 v79, v2
	v_mov_b32_e32 v80, v2
	v_mov_b32_e32 v81, v2
	v_mov_b32_e32 v90, v2
	v_mov_b32_e32 v91, v2
	v_mov_b32_e32 v92, v2
	v_mov_b32_e32 v93, v2
	v_mov_b32_e32 v94, v2
	v_mov_b32_e32 v95, v2
	v_mov_b32_e32 v96, v2
	v_mov_b32_e32 v97, v2
	v_mov_b32_e32 v106, v2
	v_mov_b32_e32 v107, v2
	v_mov_b32_e32 v108, v2
	v_mov_b32_e32 v109, v2
	v_mov_b32_e32 v110, v2
	v_mov_b32_e32 v111, v2
	v_mov_b32_e32 v112, v2
	v_mov_b32_e32 v113, v2
	v_mov_b32_e32 v122, v2
	v_mov_b32_e32 v123, v2
	v_mov_b32_e32 v124, v2
	v_mov_b32_e32 v125, v2
	v_mov_b32_e32 v126, v2
	v_mov_b32_e32 v127, v2
	v_mov_b32_e32 v128, v2
	v_mov_b32_e32 v129, v2
	v_add_u32_e32 v192, 0x18000, v195
	v_add_u32_e32 v193, 0x1c000, v195
.LBB0_651:
	ds_read_b128 v[140:143], v197
	ds_read_b128 v[144:147], v197 offset:1024
	ds_read_b128 v[148:151], v197 offset:2048
	ds_read_b128 v[152:155], v197 offset:3072
	ds_read_b128 v[156:159], v198
	ds_read_b128 v[160:163], v198 offset:1024
	ds_read_b128 v[164:167], v198 offset:2048
	ds_read_b128 v[168:171], v198 offset:3072
	s_add_u32 s28, s26, 0xfff80080
	s_addc_u32 s29, s27, -1
	s_cmp_eq_u32 s46, 28
	s_cselect_b32 s31, s15, s29
	s_cselect_b32 s30, s23, s28
	s_cselect_b32 s29, s13, s45
	s_cselect_b32 s28, s43, s44
	s_add_i32 m0, s25, 0xc000
	ds_read_b128 v[172:175], v199
	ds_read_b128 v[176:179], v199 offset:1024
	ds_read_b128 v[180:183], v199 offset:2048
	ds_read_b128 v[184:187], v199 offset:3072
	ds_read_b128 v[188:191], v199 offset:4096
	ds_read_b128 v[202:205], v199 offset:5120
	ds_read_b128 v[206:209], v199 offset:6144
	ds_read_b128 v[210:213], v199 offset:7168
	global_load_lds_dwordx4 v134, s[26:27]
	s_add_i32 m0, s25, 0xe000
	s_nop 0
	global_load_lds_dwordx4 v136, s[26:27]
	s_waitcnt vmcnt(8) lgkmcnt(0)
	s_barrier
	v_mfma_f32_16x16x32_bf16 v[126:129], v[140:143], v[172:175], v[126:129]
	v_mfma_f32_16x16x32_bf16 v[122:125], v[148:151], v[172:175], v[122:125]
	v_mfma_f32_16x16x32_bf16 v[110:113], v[140:143], v[180:183], v[110:113]
	v_mfma_f32_16x16x32_bf16 v[106:109], v[148:151], v[180:183], v[106:109]
	v_mfma_f32_16x16x32_bf16 v[94:97], v[140:143], v[188:191], v[94:97]
	v_mfma_f32_16x16x32_bf16 v[90:93], v[148:151], v[188:191], v[90:93]
	v_mfma_f32_16x16x32_bf16 v[78:81], v[140:143], v[206:209], v[78:81]
	v_mfma_f32_16x16x32_bf16 v[74:77], v[148:151], v[206:209], v[74:77]
	v_mfma_f32_16x16x32_bf16 v[126:129], v[144:147], v[176:179], v[126:129]
	v_mfma_f32_16x16x32_bf16 v[122:125], v[152:155], v[176:179], v[122:125]
	v_mfma_f32_16x16x32_bf16 v[110:113], v[144:147], v[184:187], v[110:113]
	v_mfma_f32_16x16x32_bf16 v[106:109], v[152:155], v[184:187], v[106:109]
	v_mfma_f32_16x16x32_bf16 v[94:97], v[144:147], v[202:205], v[94:97]
	v_mfma_f32_16x16x32_bf16 v[90:93], v[152:155], v[202:205], v[90:93]
	v_mfma_f32_16x16x32_bf16 v[78:81], v[144:147], v[210:213], v[78:81]
	v_mfma_f32_16x16x32_bf16 v[74:77], v[152:155], v[210:213], v[74:77]
	v_mfma_f32_16x16x32_bf16 v[118:121], v[156:159], v[172:175], v[118:121]
	v_mfma_f32_16x16x32_bf16 v[114:117], v[164:167], v[172:175], v[114:117]
	v_mfma_f32_16x16x32_bf16 v[102:105], v[156:159], v[180:183], v[102:105]
	v_mfma_f32_16x16x32_bf16 v[98:101], v[164:167], v[180:183], v[98:101]
	v_mfma_f32_16x16x32_bf16 v[86:89], v[156:159], v[188:191], v[86:89]
	v_mfma_f32_16x16x32_bf16 v[82:85], v[164:167], v[188:191], v[82:85]
	v_mfma_f32_16x16x32_bf16 v[70:73], v[156:159], v[206:209], v[70:73]
	v_mfma_f32_16x16x32_bf16 v[66:69], v[164:167], v[206:209], v[66:69]
	v_mfma_f32_16x16x32_bf16 v[118:121], v[160:163], v[176:179], v[118:121]
	v_mfma_f32_16x16x32_bf16 v[114:117], v[168:171], v[176:179], v[114:117]
	v_mfma_f32_16x16x32_bf16 v[102:105], v[160:163], v[184:187], v[102:105]
	v_mfma_f32_16x16x32_bf16 v[98:101], v[168:171], v[184:187], v[98:101]
	v_mfma_f32_16x16x32_bf16 v[86:89], v[160:163], v[202:205], v[86:89]
	v_mfma_f32_16x16x32_bf16 v[82:85], v[168:171], v[202:205], v[82:85]
	v_mfma_f32_16x16x32_bf16 v[70:73], v[160:163], v[210:213], v[70:73]
	v_mfma_f32_16x16x32_bf16 v[66:69], v[168:171], v[210:213], v[66:69]
	s_barrier
	s_add_i32 m0, s3, 0x10000
	ds_read_b128 v[172:175], v199 offset:16384
	ds_read_b128 v[176:179], v199 offset:17408
	ds_read_b128 v[180:183], v199 offset:18432
	ds_read_b128 v[184:187], v199 offset:19456
	ds_read_b128 v[188:191], v199 offset:20480
	ds_read_b128 v[202:205], v199 offset:21504
	ds_read_b128 v[206:209], v199 offset:22528
	ds_read_b128 v[210:213], v199 offset:23552
	global_load_lds_dwordx4 v130, s[28:29]
	s_add_i32 m0, s3, 0x12000
	s_add_u32 s48, s28, 0x80000
	s_addc_u32 s49, s29, 0
	global_load_lds_dwordx4 v132, s[28:29]
	s_add_i32 m0, s3, 0x14000
	s_nop 0
	global_load_lds_dwordx4 v130, s[48:49]
	s_add_i32 m0, s3, 0x16000
	s_nop 0
	global_load_lds_dwordx4 v132, s[48:49]
	s_mov_b32 m0, s25
	s_nop 0
	global_load_lds_dwordx4 v130, s[30:31]
	s_mov_b32 m0, s34
	s_nop 0
	global_load_lds_dwordx4 v132, s[30:31]
	s_waitcnt vmcnt(8) lgkmcnt(0)
	s_barrier
	v_mfma_f32_16x16x32_bf16 v[62:65], v[140:143], v[172:175], v[62:65]
	v_mfma_f32_16x16x32_bf16 v[58:61], v[148:151], v[172:175], v[58:61]
	v_mfma_f32_16x16x32_bf16 v[46:49], v[140:143], v[180:183], v[46:49]
	v_mfma_f32_16x16x32_bf16 v[42:45], v[148:151], v[180:183], v[42:45]
	v_mfma_f32_16x16x32_bf16 v[30:33], v[140:143], v[188:191], v[30:33]
	v_mfma_f32_16x16x32_bf16 v[26:29], v[148:151], v[188:191], v[26:29]
	v_mfma_f32_16x16x32_bf16 v[14:17], v[140:143], v[206:209], v[14:17]
	v_mfma_f32_16x16x32_bf16 v[10:13], v[148:151], v[206:209], v[10:13]
	v_mfma_f32_16x16x32_bf16 v[62:65], v[144:147], v[176:179], v[62:65]
	v_mfma_f32_16x16x32_bf16 v[58:61], v[152:155], v[176:179], v[58:61]
	v_mfma_f32_16x16x32_bf16 v[46:49], v[144:147], v[184:187], v[46:49]
	v_mfma_f32_16x16x32_bf16 v[42:45], v[152:155], v[184:187], v[42:45]
	v_mfma_f32_16x16x32_bf16 v[30:33], v[144:147], v[202:205], v[30:33]
	v_mfma_f32_16x16x32_bf16 v[26:29], v[152:155], v[202:205], v[26:29]
	v_mfma_f32_16x16x32_bf16 v[14:17], v[144:147], v[210:213], v[14:17]
	v_mfma_f32_16x16x32_bf16 v[10:13], v[152:155], v[210:213], v[10:13]
	v_mfma_f32_16x16x32_bf16 v[54:57], v[156:159], v[172:175], v[54:57]
	v_mfma_f32_16x16x32_bf16 v[50:53], v[164:167], v[172:175], v[50:53]
	v_mfma_f32_16x16x32_bf16 v[38:41], v[156:159], v[180:183], v[38:41]
	v_mfma_f32_16x16x32_bf16 v[34:37], v[164:167], v[180:183], v[34:37]
	v_mfma_f32_16x16x32_bf16 v[22:25], v[156:159], v[188:191], v[22:25]
	v_mfma_f32_16x16x32_bf16 v[18:21], v[164:167], v[188:191], v[18:21]
	v_mfma_f32_16x16x32_bf16 v[6:9], v[156:159], v[206:209], v[6:9]
	v_mfma_f32_16x16x32_bf16 v[2:5], v[164:167], v[206:209], v[2:5]
	v_mfma_f32_16x16x32_bf16 v[54:57], v[160:163], v[176:179], v[54:57]
	v_mfma_f32_16x16x32_bf16 v[50:53], v[168:171], v[176:179], v[50:53]
	v_mfma_f32_16x16x32_bf16 v[38:41], v[160:163], v[184:187], v[38:41]
	v_mfma_f32_16x16x32_bf16 v[34:37], v[168:171], v[184:187], v[34:37]
	v_mfma_f32_16x16x32_bf16 v[22:25], v[160:163], v[202:205], v[22:25]
	v_mfma_f32_16x16x32_bf16 v[18:21], v[168:171], v[202:205], v[18:21]
	v_mfma_f32_16x16x32_bf16 v[6:9], v[160:163], v[210:213], v[6:9]
	v_mfma_f32_16x16x32_bf16 v[2:5], v[168:171], v[210:213], v[2:5]
	s_barrier
	ds_read_b128 v[140:143], v192
	ds_read_b128 v[144:147], v192 offset:1024
	ds_read_b128 v[148:151], v192 offset:2048
	ds_read_b128 v[152:155], v192 offset:3072
	ds_read_b128 v[156:159], v193
	ds_read_b128 v[160:163], v193 offset:1024
	ds_read_b128 v[164:167], v193 offset:2048
	ds_read_b128 v[168:171], v193 offset:3072
	s_add_u32 s30, s30, 0x80000
	s_addc_u32 s31, s31, 0
	s_mov_b32 m0, s35
	ds_read_b128 v[172:175], v199 offset:32768
	ds_read_b128 v[176:179], v199 offset:33792
	ds_read_b128 v[180:183], v199 offset:34816
	ds_read_b128 v[184:187], v199 offset:35840
	ds_read_b128 v[188:191], v199 offset:36864
	ds_read_b128 v[202:205], v199 offset:37888
	ds_read_b128 v[206:209], v199 offset:38912
	ds_read_b128 v[210:213], v199 offset:39936
	global_load_lds_dwordx4 v130, s[30:31]
	s_mov_b32 m0, s36
	s_nop 0
	global_load_lds_dwordx4 v132, s[30:31]
	s_waitcnt vmcnt(8) lgkmcnt(0)
	s_barrier
	v_mfma_f32_16x16x32_bf16 v[126:129], v[140:143], v[172:175], v[126:129]
	v_mfma_f32_16x16x32_bf16 v[122:125], v[148:151], v[172:175], v[122:125]
	v_mfma_f32_16x16x32_bf16 v[110:113], v[140:143], v[180:183], v[110:113]
	v_mfma_f32_16x16x32_bf16 v[106:109], v[148:151], v[180:183], v[106:109]
	v_mfma_f32_16x16x32_bf16 v[94:97], v[140:143], v[188:191], v[94:97]
	v_mfma_f32_16x16x32_bf16 v[90:93], v[148:151], v[188:191], v[90:93]
	v_mfma_f32_16x16x32_bf16 v[78:81], v[140:143], v[206:209], v[78:81]
	v_mfma_f32_16x16x32_bf16 v[74:77], v[148:151], v[206:209], v[74:77]
	v_mfma_f32_16x16x32_bf16 v[126:129], v[144:147], v[176:179], v[126:129]
	v_mfma_f32_16x16x32_bf16 v[122:125], v[152:155], v[176:179], v[122:125]
	v_mfma_f32_16x16x32_bf16 v[110:113], v[144:147], v[184:187], v[110:113]
	v_mfma_f32_16x16x32_bf16 v[106:109], v[152:155], v[184:187], v[106:109]
	v_mfma_f32_16x16x32_bf16 v[94:97], v[144:147], v[202:205], v[94:97]
	v_mfma_f32_16x16x32_bf16 v[90:93], v[152:155], v[202:205], v[90:93]
	v_mfma_f32_16x16x32_bf16 v[78:81], v[144:147], v[210:213], v[78:81]
	v_mfma_f32_16x16x32_bf16 v[74:77], v[152:155], v[210:213], v[74:77]
	v_mfma_f32_16x16x32_bf16 v[118:121], v[156:159], v[172:175], v[118:121]
	v_mfma_f32_16x16x32_bf16 v[114:117], v[164:167], v[172:175], v[114:117]
	v_mfma_f32_16x16x32_bf16 v[102:105], v[156:159], v[180:183], v[102:105]
	v_mfma_f32_16x16x32_bf16 v[98:101], v[164:167], v[180:183], v[98:101]
	v_mfma_f32_16x16x32_bf16 v[86:89], v[156:159], v[188:191], v[86:89]
	v_mfma_f32_16x16x32_bf16 v[82:85], v[164:167], v[188:191], v[82:85]
	v_mfma_f32_16x16x32_bf16 v[70:73], v[156:159], v[206:209], v[70:73]
	v_mfma_f32_16x16x32_bf16 v[66:69], v[164:167], v[206:209], v[66:69]
	v_mfma_f32_16x16x32_bf16 v[118:121], v[160:163], v[176:179], v[118:121]
	v_mfma_f32_16x16x32_bf16 v[114:117], v[168:171], v[176:179], v[114:117]
	v_mfma_f32_16x16x32_bf16 v[102:105], v[160:163], v[184:187], v[102:105]
	v_mfma_f32_16x16x32_bf16 v[98:101], v[168:171], v[184:187], v[98:101]
	v_mfma_f32_16x16x32_bf16 v[86:89], v[160:163], v[202:205], v[86:89]
	v_mfma_f32_16x16x32_bf16 v[82:85], v[168:171], v[202:205], v[82:85]
	v_mfma_f32_16x16x32_bf16 v[70:73], v[160:163], v[210:213], v[70:73]
	v_mfma_f32_16x16x32_bf16 v[66:69], v[168:171], v[210:213], v[66:69]
	s_barrier
	s_add_u32 s98, s30, 0xfff80080
	s_addc_u32 s99, s31, -1
	s_add_i32 m0, s3, 0x18000
	ds_read_b128 v[172:175], v199 offset:49152
	ds_read_b128 v[176:179], v199 offset:50176
	ds_read_b128 v[180:183], v199 offset:51200
	ds_read_b128 v[184:187], v199 offset:52224
	ds_read_b128 v[188:191], v199 offset:53248
	ds_read_b128 v[202:205], v199 offset:54272
	ds_read_b128 v[206:209], v199 offset:55296
	ds_read_b128 v[210:213], v199 offset:56320
	s_add_u32 s100, s28, 0x80
	s_addc_u32 s101, s29, 0
	global_load_lds_dwordx4 v130, s[100:101]
	s_add_i32 m0, s3, 0x1a000
	s_add_u32 s28, s28, 0x80080
	s_addc_u32 s29, s29, 0
	global_load_lds_dwordx4 v132, s[100:101]
	s_add_i32 m0, s3, 0x1c000
	s_nop 0
	global_load_lds_dwordx4 v130, s[28:29]
	s_add_i32 m0, s3, 0x1e000
	s_nop 0
	global_load_lds_dwordx4 v132, s[28:29]
	s_mov_b32 m0, s38
	s_nop 0
	global_load_lds_dwordx4 v130, s[98:99]
	s_mov_b32 m0, s39
	s_nop 0
	global_load_lds_dwordx4 v132, s[98:99]
	s_waitcnt vmcnt(8) lgkmcnt(0)
	s_barrier
	v_mfma_f32_16x16x32_bf16 v[62:65], v[140:143], v[172:175], v[62:65]
	v_mfma_f32_16x16x32_bf16 v[58:61], v[148:151], v[172:175], v[58:61]
	v_mfma_f32_16x16x32_bf16 v[46:49], v[140:143], v[180:183], v[46:49]
	v_mfma_f32_16x16x32_bf16 v[42:45], v[148:151], v[180:183], v[42:45]
	v_mfma_f32_16x16x32_bf16 v[30:33], v[140:143], v[188:191], v[30:33]
	v_mfma_f32_16x16x32_bf16 v[26:29], v[148:151], v[188:191], v[26:29]
	v_mfma_f32_16x16x32_bf16 v[14:17], v[140:143], v[206:209], v[14:17]
	v_mfma_f32_16x16x32_bf16 v[10:13], v[148:151], v[206:209], v[10:13]
	v_mfma_f32_16x16x32_bf16 v[62:65], v[144:147], v[176:179], v[62:65]
	v_mfma_f32_16x16x32_bf16 v[58:61], v[152:155], v[176:179], v[58:61]
	v_mfma_f32_16x16x32_bf16 v[46:49], v[144:147], v[184:187], v[46:49]
	v_mfma_f32_16x16x32_bf16 v[42:45], v[152:155], v[184:187], v[42:45]
	v_mfma_f32_16x16x32_bf16 v[30:33], v[144:147], v[202:205], v[30:33]
	v_mfma_f32_16x16x32_bf16 v[26:29], v[152:155], v[202:205], v[26:29]
	v_mfma_f32_16x16x32_bf16 v[14:17], v[144:147], v[210:213], v[14:17]
	v_mfma_f32_16x16x32_bf16 v[10:13], v[152:155], v[210:213], v[10:13]
	v_mfma_f32_16x16x32_bf16 v[54:57], v[156:159], v[172:175], v[54:57]
	v_mfma_f32_16x16x32_bf16 v[50:53], v[164:167], v[172:175], v[50:53]
	v_mfma_f32_16x16x32_bf16 v[38:41], v[156:159], v[180:183], v[38:41]
	v_mfma_f32_16x16x32_bf16 v[34:37], v[164:167], v[180:183], v[34:37]
	v_mfma_f32_16x16x32_bf16 v[22:25], v[156:159], v[188:191], v[22:25]
	v_mfma_f32_16x16x32_bf16 v[18:21], v[164:167], v[188:191], v[18:21]
	v_mfma_f32_16x16x32_bf16 v[6:9], v[156:159], v[206:209], v[6:9]
	v_mfma_f32_16x16x32_bf16 v[2:5], v[164:167], v[206:209], v[2:5]
	v_mfma_f32_16x16x32_bf16 v[54:57], v[160:163], v[176:179], v[54:57]
	v_mfma_f32_16x16x32_bf16 v[50:53], v[168:171], v[176:179], v[50:53]
	v_mfma_f32_16x16x32_bf16 v[38:41], v[160:163], v[184:187], v[38:41]
	v_mfma_f32_16x16x32_bf16 v[34:37], v[168:171], v[184:187], v[34:37]
	v_mfma_f32_16x16x32_bf16 v[22:25], v[160:163], v[202:205], v[22:25]
	v_mfma_f32_16x16x32_bf16 v[18:21], v[168:171], v[202:205], v[18:21]
	v_mfma_f32_16x16x32_bf16 v[6:9], v[160:163], v[210:213], v[6:9]
	v_mfma_f32_16x16x32_bf16 v[2:5], v[168:171], v[210:213], v[2:5]
	s_barrier
	s_add_i32 s46, s46, 2
	s_add_u32 s44, s44, 0x100
	s_addc_u32 s45, s45, 0
	s_add_u32 s26, s26, 0x100
	s_addc_u32 s27, s27, 0
	s_cmp_gt_u32 s46, 29
	s_cbranch_scc0 .LBB0_651
	s_and_b64 vcc, exec, s[10:11]
	s_cbranch_vccz .LBB0_654
	s_barrier

.LBB0_807:
	s_mov_b32 s18, s19
	s_ashr_i32 s19, s19, 31
	s_lshl_b64 s[22:23], s[18:19], 20
	s_add_u32 s22, s70, s22
	s_addc_u32 s23, s71, s23
	s_and_b64 s[24:25], s[20:21], exec
	s_mov_b32 s16, s17
	s_cselect_b32 s19, s23, s35
	s_cselect_b32 s51, s22, s34
	s_ashr_i32 s17, s17, 31
	s_lshl_b64 s[24:25], s[16:17], 20
	s_add_u32 s24, s84, s24
	s_addc_u32 s25, s85, s25
	s_and_b64 s[36:37], s[20:21], exec
	s_cselect_b32 s17, s25, s31
	s_cselect_b32 s52, s24, s30
	s_add_u32 s53, s30, 0x100
	s_addc_u32 s54, s31, 0
	s_add_u32 s30, s34, 0x80080
	v_mov_b32_e32 v2, 0
	s_addc_u32 s31, s35, 0
	s_mov_b32 s55, -2
	v_mov_b32_e32 v3, v2
	v_mov_b32_e32 v4, v2
	v_mov_b32_e32 v5, v2
	v_mov_b32_e32 v6, v2
	v_mov_b32_e32 v7, v2
	v_mov_b32_e32 v8, v2
	v_mov_b32_e32 v9, v2
	v_mov_b32_e32 v18, v2
	v_mov_b32_e32 v19, v2
	v_mov_b32_e32 v20, v2
	v_mov_b32_e32 v21, v2
	v_mov_b32_e32 v22, v2
	v_mov_b32_e32 v23, v2
	v_mov_b32_e32 v24, v2
	v_mov_b32_e32 v25, v2
	v_mov_b32_e32 v34, v2
	v_mov_b32_e32 v35, v2
	v_mov_b32_e32 v36, v2
	v_mov_b32_e32 v37, v2
	v_mov_b32_e32 v38, v2
	v_mov_b32_e32 v39, v2
	v_mov_b32_e32 v40, v2
	v_mov_b32_e32 v41, v2
	v_mov_b32_e32 v50, v2
	v_mov_b32_e32 v51, v2
	v_mov_b32_e32 v52, v2
	v_mov_b32_e32 v53, v2
	v_mov_b32_e32 v54, v2
	v_mov_b32_e32 v55, v2
	v_mov_b32_e32 v56, v2
	v_mov_b32_e32 v57, v2
	v_mov_b32_e32 v10, v2
	v_mov_b32_e32 v11, v2
	v_mov_b32_e32 v12, v2
	v_mov_b32_e32 v13, v2
	v_mov_b32_e32 v14, v2
	v_mov_b32_e32 v15, v2
	v_mov_b32_e32 v16, v2
	v_mov_b32_e32 v17, v2
	v_mov_b32_e32 v26, v2
	v_mov_b32_e32 v27, v2
	v_mov_b32_e32 v28, v2
	v_mov_b32_e32 v29, v2
	v_mov_b32_e32 v30, v2
	v_mov_b32_e32 v31, v2
	v_mov_b32_e32 v32, v2
	v_mov_b32_e32 v33, v2
	v_mov_b32_e32 v42, v2
	v_mov_b32_e32 v43, v2
	v_mov_b32_e32 v44, v2
	v_mov_b32_e32 v45, v2
	v_mov_b32_e32 v46, v2
	v_mov_b32_e32 v47, v2
	v_mov_b32_e32 v48, v2
	v_mov_b32_e32 v49, v2
	v_mov_b32_e32 v58, v2
	v_mov_b32_e32 v59, v2
	v_mov_b32_e32 v60, v2
	v_mov_b32_e32 v61, v2
	v_mov_b32_e32 v62, v2
	v_mov_b32_e32 v63, v2
	v_mov_b32_e32 v64, v2
	v_mov_b32_e32 v65, v2
	v_mov_b32_e32 v66, v2
	v_mov_b32_e32 v67, v2
	v_mov_b32_e32 v68, v2
	v_mov_b32_e32 v69, v2
	v_mov_b32_e32 v70, v2
	v_mov_b32_e32 v71, v2
	v_mov_b32_e32 v72, v2
	v_mov_b32_e32 v73, v2
	v_mov_b32_e32 v82, v2
	v_mov_b32_e32 v83, v2
	v_mov_b32_e32 v84, v2
	v_mov_b32_e32 v85, v2
	v_mov_b32_e32 v86, v2
	v_mov_b32_e32 v87, v2
	v_mov_b32_e32 v88, v2
	v_mov_b32_e32 v89, v2
	v_mov_b32_e32 v98, v2
	v_mov_b32_e32 v99, v2
	v_mov_b32_e32 v100, v2
	v_mov_b32_e32 v101, v2
	v_mov_b32_e32 v102, v2
	v_mov_b32_e32 v103, v2
	v_mov_b32_e32 v104, v2
	v_mov_b32_e32 v105, v2
	v_mov_b32_e32 v114, v2
	v_mov_b32_e32 v115, v2
	v_mov_b32_e32 v116, v2
	v_mov_b32_e32 v117, v2
	v_mov_b32_e32 v118, v2
	v_mov_b32_e32 v119, v2
	v_mov_b32_e32 v120, v2
	v_mov_b32_e32 v121, v2
	v_mov_b32_e32 v74, v2
	v_mov_b32_e32 v75, v2
	v_mov_b32_e32 v76, v2
	v_mov_b32_e32 v77, v2
	v_mov_b32_e32 v78, v2
	v_mov_b32_e32 v79, v2
	v_mov_b32_e32 v80, v2
	v_mov_b32_e32 v81, v2
	v_mov_b32_e32 v90, v2
	v_mov_b32_e32 v91, v2
	v_mov_b32_e32 v92, v2
	v_mov_b32_e32 v93, v2
	v_mov_b32_e32 v94, v2
	v_mov_b32_e32 v95, v2
	v_mov_b32_e32 v96, v2
	v_mov_b32_e32 v97, v2
	v_mov_b32_e32 v106, v2
	v_mov_b32_e32 v107, v2
	v_mov_b32_e32 v108, v2
	v_mov_b32_e32 v109, v2
	v_mov_b32_e32 v110, v2
	v_mov_b32_e32 v111, v2
	v_mov_b32_e32 v112, v2
	v_mov_b32_e32 v113, v2
	v_mov_b32_e32 v122, v2
	v_mov_b32_e32 v123, v2
	v_mov_b32_e32 v124, v2
	v_mov_b32_e32 v125, v2
	v_mov_b32_e32 v126, v2
	v_mov_b32_e32 v127, v2
	v_mov_b32_e32 v128, v2
	v_mov_b32_e32 v129, v2
	v_add_u32_e32 v148, 0x18000, v150
	v_add_u32_e32 v149, 0x1c000, v150
.LBB0_808:
	ds_read_b128 v[144:147], v152
	ds_read_b128 v[156:159], v152 offset:1024
	ds_read_b128 v[160:163], v152 offset:2048
	ds_read_b128 v[164:167], v152 offset:3072
	ds_read_b128 v[168:171], v153
	ds_read_b128 v[172:175], v153 offset:1024
	ds_read_b128 v[176:179], v153 offset:2048
	ds_read_b128 v[180:183], v153 offset:3072
	s_add_u32 s34, s30, 0xfff80080
	s_addc_u32 s35, s31, -1
	s_cmp_eq_u32 s55, 28
	s_cselect_b32 s37, s19, s35
	s_cselect_b32 s36, s51, s34
	s_cselect_b32 s35, s17, s54
	s_cselect_b32 s34, s52, s53
	s_add_i32 m0, s27, 0xc000
	ds_read_b128 v[184:187], v154
	ds_read_b128 v[188:191], v154 offset:1024
	ds_read_b128 v[196:199], v154 offset:2048
	ds_read_b128 v[200:203], v154 offset:3072
	ds_read_b128 v[204:207], v154 offset:4096
	ds_read_b128 v[208:211], v154 offset:5120
	ds_read_b128 v[212:215], v154 offset:6144
	ds_read_b128 v[216:219], v154 offset:7168
	global_load_lds_dwordx4 v138, s[30:31]
	s_add_i32 m0, s27, 0xe000
	s_nop 0
	global_load_lds_dwordx4 v140, s[30:31]
	s_waitcnt vmcnt(8) lgkmcnt(0)
	s_barrier
	v_mfma_f32_16x16x32_bf16 v[126:129], v[144:147], v[184:187], v[126:129]
	v_mfma_f32_16x16x32_bf16 v[122:125], v[160:163], v[184:187], v[122:125]
	v_mfma_f32_16x16x32_bf16 v[110:113], v[144:147], v[196:199], v[110:113]
	v_mfma_f32_16x16x32_bf16 v[106:109], v[160:163], v[196:199], v[106:109]
	v_mfma_f32_16x16x32_bf16 v[94:97], v[144:147], v[204:207], v[94:97]
	v_mfma_f32_16x16x32_bf16 v[90:93], v[160:163], v[204:207], v[90:93]
	v_mfma_f32_16x16x32_bf16 v[78:81], v[144:147], v[212:215], v[78:81]
	v_mfma_f32_16x16x32_bf16 v[74:77], v[160:163], v[212:215], v[74:77]
	v_mfma_f32_16x16x32_bf16 v[126:129], v[156:159], v[188:191], v[126:129]
	v_mfma_f32_16x16x32_bf16 v[122:125], v[164:167], v[188:191], v[122:125]
	v_mfma_f32_16x16x32_bf16 v[110:113], v[156:159], v[200:203], v[110:113]
	v_mfma_f32_16x16x32_bf16 v[106:109], v[164:167], v[200:203], v[106:109]
	v_mfma_f32_16x16x32_bf16 v[94:97], v[156:159], v[208:211], v[94:97]
	v_mfma_f32_16x16x32_bf16 v[90:93], v[164:167], v[208:211], v[90:93]
	v_mfma_f32_16x16x32_bf16 v[78:81], v[156:159], v[216:219], v[78:81]
	v_mfma_f32_16x16x32_bf16 v[74:77], v[164:167], v[216:219], v[74:77]
	v_mfma_f32_16x16x32_bf16 v[118:121], v[168:171], v[184:187], v[118:121]
	v_mfma_f32_16x16x32_bf16 v[114:117], v[176:179], v[184:187], v[114:117]
	v_mfma_f32_16x16x32_bf16 v[102:105], v[168:171], v[196:199], v[102:105]
	v_mfma_f32_16x16x32_bf16 v[98:101], v[176:179], v[196:199], v[98:101]
	v_mfma_f32_16x16x32_bf16 v[86:89], v[168:171], v[204:207], v[86:89]
	v_mfma_f32_16x16x32_bf16 v[82:85], v[176:179], v[204:207], v[82:85]
	v_mfma_f32_16x16x32_bf16 v[70:73], v[168:171], v[212:215], v[70:73]
	v_mfma_f32_16x16x32_bf16 v[66:69], v[176:179], v[212:215], v[66:69]
	v_mfma_f32_16x16x32_bf16 v[118:121], v[172:175], v[188:191], v[118:121]
	v_mfma_f32_16x16x32_bf16 v[114:117], v[180:183], v[188:191], v[114:117]
	v_mfma_f32_16x16x32_bf16 v[102:105], v[172:175], v[200:203], v[102:105]
	v_mfma_f32_16x16x32_bf16 v[98:101], v[180:183], v[200:203], v[98:101]
	v_mfma_f32_16x16x32_bf16 v[86:89], v[172:175], v[208:211], v[86:89]
	v_mfma_f32_16x16x32_bf16 v[82:85], v[180:183], v[208:211], v[82:85]
	v_mfma_f32_16x16x32_bf16 v[70:73], v[172:175], v[216:219], v[70:73]
	v_mfma_f32_16x16x32_bf16 v[66:69], v[180:183], v[216:219], v[66:69]
	s_barrier
	s_add_i32 m0, s38, 0x10000
	ds_read_b128 v[184:187], v154 offset:16384
	ds_read_b128 v[188:191], v154 offset:17408
	ds_read_b128 v[196:199], v154 offset:18432
	ds_read_b128 v[200:203], v154 offset:19456
	ds_read_b128 v[204:207], v154 offset:20480
	ds_read_b128 v[208:211], v154 offset:21504
	ds_read_b128 v[212:215], v154 offset:22528
	ds_read_b128 v[216:219], v154 offset:23552
	global_load_lds_dwordx4 v132, s[34:35]
	s_add_i32 m0, s38, 0x12000
	s_add_u32 s56, s34, 0x80000
	s_addc_u32 s57, s35, 0
	global_load_lds_dwordx4 v136, s[34:35]
	s_add_i32 m0, s38, 0x14000
	s_nop 0
	global_load_lds_dwordx4 v132, s[56:57]
	s_add_i32 m0, s38, 0x16000
	s_nop 0
	global_load_lds_dwordx4 v136, s[56:57]
	s_mov_b32 m0, s27
	s_nop 0
	global_load_lds_dwordx4 v130, s[36:37]
	s_mov_b32 m0, s29
	s_nop 0
	global_load_lds_dwordx4 v134, s[36:37]
	s_waitcnt vmcnt(8) lgkmcnt(0)
	s_barrier
	v_mfma_f32_16x16x32_bf16 v[62:65], v[144:147], v[184:187], v[62:65]
	v_mfma_f32_16x16x32_bf16 v[58:61], v[160:163], v[184:187], v[58:61]
	v_mfma_f32_16x16x32_bf16 v[46:49], v[144:147], v[196:199], v[46:49]
	v_mfma_f32_16x16x32_bf16 v[42:45], v[160:163], v[196:199], v[42:45]
	v_mfma_f32_16x16x32_bf16 v[30:33], v[144:147], v[204:207], v[30:33]
	v_mfma_f32_16x16x32_bf16 v[26:29], v[160:163], v[204:207], v[26:29]
	v_mfma_f32_16x16x32_bf16 v[14:17], v[144:147], v[212:215], v[14:17]
	v_mfma_f32_16x16x32_bf16 v[10:13], v[160:163], v[212:215], v[10:13]
	v_mfma_f32_16x16x32_bf16 v[62:65], v[156:159], v[188:191], v[62:65]
	v_mfma_f32_16x16x32_bf16 v[58:61], v[164:167], v[188:191], v[58:61]
	v_mfma_f32_16x16x32_bf16 v[46:49], v[156:159], v[200:203], v[46:49]
	v_mfma_f32_16x16x32_bf16 v[42:45], v[164:167], v[200:203], v[42:45]
	v_mfma_f32_16x16x32_bf16 v[30:33], v[156:159], v[208:211], v[30:33]
	v_mfma_f32_16x16x32_bf16 v[26:29], v[164:167], v[208:211], v[26:29]
	v_mfma_f32_16x16x32_bf16 v[14:17], v[156:159], v[216:219], v[14:17]
	v_mfma_f32_16x16x32_bf16 v[10:13], v[164:167], v[216:219], v[10:13]
	v_mfma_f32_16x16x32_bf16 v[54:57], v[168:171], v[184:187], v[54:57]
	v_mfma_f32_16x16x32_bf16 v[50:53], v[176:179], v[184:187], v[50:53]
	v_mfma_f32_16x16x32_bf16 v[38:41], v[168:171], v[196:199], v[38:41]
	v_mfma_f32_16x16x32_bf16 v[34:37], v[176:179], v[196:199], v[34:37]
	v_mfma_f32_16x16x32_bf16 v[22:25], v[168:171], v[204:207], v[22:25]
	v_mfma_f32_16x16x32_bf16 v[18:21], v[176:179], v[204:207], v[18:21]
	v_mfma_f32_16x16x32_bf16 v[6:9], v[168:171], v[212:215], v[6:9]
	v_mfma_f32_16x16x32_bf16 v[2:5], v[176:179], v[212:215], v[2:5]
	v_mfma_f32_16x16x32_bf16 v[54:57], v[172:175], v[188:191], v[54:57]
	v_mfma_f32_16x16x32_bf16 v[50:53], v[180:183], v[188:191], v[50:53]
	v_mfma_f32_16x16x32_bf16 v[38:41], v[172:175], v[200:203], v[38:41]
	v_mfma_f32_16x16x32_bf16 v[34:37], v[180:183], v[200:203], v[34:37]
	v_mfma_f32_16x16x32_bf16 v[22:25], v[172:175], v[208:211], v[22:25]
	v_mfma_f32_16x16x32_bf16 v[18:21], v[180:183], v[208:211], v[18:21]
	v_mfma_f32_16x16x32_bf16 v[6:9], v[172:175], v[216:219], v[6:9]
	v_mfma_f32_16x16x32_bf16 v[2:5], v[180:183], v[216:219], v[2:5]
	s_barrier
	ds_read_b128 v[144:147], v148
	ds_read_b128 v[156:159], v148 offset:1024
	ds_read_b128 v[160:163], v148 offset:2048
	ds_read_b128 v[164:167], v148 offset:3072
	ds_read_b128 v[168:171], v149
	ds_read_b128 v[172:175], v149 offset:1024
	ds_read_b128 v[176:179], v149 offset:2048
	ds_read_b128 v[180:183], v149 offset:3072
	s_add_u32 s36, s36, 0x80000
	s_addc_u32 s37, s37, 0
	s_mov_b32 m0, s39
	ds_read_b128 v[184:187], v154 offset:32768
	ds_read_b128 v[188:191], v154 offset:33792
	ds_read_b128 v[196:199], v154 offset:34816
	ds_read_b128 v[200:203], v154 offset:35840
	ds_read_b128 v[204:207], v154 offset:36864
	ds_read_b128 v[208:211], v154 offset:37888
	ds_read_b128 v[212:215], v154 offset:38912
	ds_read_b128 v[216:219], v154 offset:39936
	global_load_lds_dwordx4 v130, s[36:37]
	s_mov_b32 m0, s40
	s_nop 0
	global_load_lds_dwordx4 v134, s[36:37]
	s_waitcnt vmcnt(8) lgkmcnt(0)
	s_barrier
	v_mfma_f32_16x16x32_bf16 v[126:129], v[144:147], v[184:187], v[126:129]
	v_mfma_f32_16x16x32_bf16 v[122:125], v[160:163], v[184:187], v[122:125]
	v_mfma_f32_16x16x32_bf16 v[110:113], v[144:147], v[196:199], v[110:113]
	v_mfma_f32_16x16x32_bf16 v[106:109], v[160:163], v[196:199], v[106:109]
	v_mfma_f32_16x16x32_bf16 v[94:97], v[144:147], v[204:207], v[94:97]
	v_mfma_f32_16x16x32_bf16 v[90:93], v[160:163], v[204:207], v[90:93]
	v_mfma_f32_16x16x32_bf16 v[78:81], v[144:147], v[212:215], v[78:81]
	v_mfma_f32_16x16x32_bf16 v[74:77], v[160:163], v[212:215], v[74:77]
	v_mfma_f32_16x16x32_bf16 v[126:129], v[156:159], v[188:191], v[126:129]
	v_mfma_f32_16x16x32_bf16 v[122:125], v[164:167], v[188:191], v[122:125]
	v_mfma_f32_16x16x32_bf16 v[110:113], v[156:159], v[200:203], v[110:113]
	v_mfma_f32_16x16x32_bf16 v[106:109], v[164:167], v[200:203], v[106:109]
	v_mfma_f32_16x16x32_bf16 v[94:97], v[156:159], v[208:211], v[94:97]
	v_mfma_f32_16x16x32_bf16 v[90:93], v[164:167], v[208:211], v[90:93]
	v_mfma_f32_16x16x32_bf16 v[78:81], v[156:159], v[216:219], v[78:81]
	v_mfma_f32_16x16x32_bf16 v[74:77], v[164:167], v[216:219], v[74:77]
	v_mfma_f32_16x16x32_bf16 v[118:121], v[168:171], v[184:187], v[118:121]
	v_mfma_f32_16x16x32_bf16 v[114:117], v[176:179], v[184:187], v[114:117]
	v_mfma_f32_16x16x32_bf16 v[102:105], v[168:171], v[196:199], v[102:105]
	v_mfma_f32_16x16x32_bf16 v[98:101], v[176:179], v[196:199], v[98:101]
	v_mfma_f32_16x16x32_bf16 v[86:89], v[168:171], v[204:207], v[86:89]
	v_mfma_f32_16x16x32_bf16 v[82:85], v[176:179], v[204:207], v[82:85]
	v_mfma_f32_16x16x32_bf16 v[70:73], v[168:171], v[212:215], v[70:73]
	v_mfma_f32_16x16x32_bf16 v[66:69], v[176:179], v[212:215], v[66:69]
	v_mfma_f32_16x16x32_bf16 v[118:121], v[172:175], v[188:191], v[118:121]
	v_mfma_f32_16x16x32_bf16 v[114:117], v[180:183], v[188:191], v[114:117]
	v_mfma_f32_16x16x32_bf16 v[102:105], v[172:175], v[200:203], v[102:105]
	v_mfma_f32_16x16x32_bf16 v[98:101], v[180:183], v[200:203], v[98:101]
	v_mfma_f32_16x16x32_bf16 v[86:89], v[172:175], v[208:211], v[86:89]
	v_mfma_f32_16x16x32_bf16 v[82:85], v[180:183], v[208:211], v[82:85]
	v_mfma_f32_16x16x32_bf16 v[70:73], v[172:175], v[216:219], v[70:73]
	v_mfma_f32_16x16x32_bf16 v[66:69], v[180:183], v[216:219], v[66:69]
	s_barrier
	s_add_u32 s98, s36, 0xfff80080
	s_addc_u32 s99, s37, -1
	s_add_i32 m0, s38, 0x18000
	ds_read_b128 v[184:187], v154 offset:49152
	ds_read_b128 v[188:191], v154 offset:50176
	ds_read_b128 v[196:199], v154 offset:51200
	ds_read_b128 v[200:203], v154 offset:52224
	ds_read_b128 v[204:207], v154 offset:53248
	ds_read_b128 v[208:211], v154 offset:54272
	ds_read_b128 v[212:215], v154 offset:55296
	ds_read_b128 v[216:219], v154 offset:56320
	s_add_u32 s100, s34, 0x80
	s_addc_u32 s101, s35, 0
	global_load_lds_dwordx4 v132, s[100:101]
	s_add_i32 m0, s38, 0x1a000
	s_add_u32 s34, s34, 0x80080
	s_addc_u32 s35, s35, 0
	global_load_lds_dwordx4 v136, s[100:101]
	s_add_i32 m0, s38, 0x1c000
	s_nop 0
	global_load_lds_dwordx4 v132, s[34:35]
	s_add_i32 m0, s38, 0x1e000
	s_nop 0
	global_load_lds_dwordx4 v136, s[34:35]
	s_mov_b32 m0, s42
	s_nop 0
	global_load_lds_dwordx4 v130, s[98:99]
	s_mov_b32 m0, s43
	s_nop 0
	global_load_lds_dwordx4 v134, s[98:99]
	s_waitcnt vmcnt(8) lgkmcnt(0)
	s_barrier
	v_mfma_f32_16x16x32_bf16 v[62:65], v[144:147], v[184:187], v[62:65]
	v_mfma_f32_16x16x32_bf16 v[58:61], v[160:163], v[184:187], v[58:61]
	v_mfma_f32_16x16x32_bf16 v[46:49], v[144:147], v[196:199], v[46:49]
	v_mfma_f32_16x16x32_bf16 v[42:45], v[160:163], v[196:199], v[42:45]
	v_mfma_f32_16x16x32_bf16 v[30:33], v[144:147], v[204:207], v[30:33]
	v_mfma_f32_16x16x32_bf16 v[26:29], v[160:163], v[204:207], v[26:29]
	v_mfma_f32_16x16x32_bf16 v[14:17], v[144:147], v[212:215], v[14:17]
	v_mfma_f32_16x16x32_bf16 v[10:13], v[160:163], v[212:215], v[10:13]
	v_mfma_f32_16x16x32_bf16 v[62:65], v[156:159], v[188:191], v[62:65]
	v_mfma_f32_16x16x32_bf16 v[58:61], v[164:167], v[188:191], v[58:61]
	v_mfma_f32_16x16x32_bf16 v[46:49], v[156:159], v[200:203], v[46:49]
	v_mfma_f32_16x16x32_bf16 v[42:45], v[164:167], v[200:203], v[42:45]
	v_mfma_f32_16x16x32_bf16 v[30:33], v[156:159], v[208:211], v[30:33]
	v_mfma_f32_16x16x32_bf16 v[26:29], v[164:167], v[208:211], v[26:29]
	v_mfma_f32_16x16x32_bf16 v[14:17], v[156:159], v[216:219], v[14:17]
	v_mfma_f32_16x16x32_bf16 v[10:13], v[164:167], v[216:219], v[10:13]
	v_mfma_f32_16x16x32_bf16 v[54:57], v[168:171], v[184:187], v[54:57]
	v_mfma_f32_16x16x32_bf16 v[50:53], v[176:179], v[184:187], v[50:53]
	v_mfma_f32_16x16x32_bf16 v[38:41], v[168:171], v[196:199], v[38:41]
	v_mfma_f32_16x16x32_bf16 v[34:37], v[176:179], v[196:199], v[34:37]
	v_mfma_f32_16x16x32_bf16 v[22:25], v[168:171], v[204:207], v[22:25]
	v_mfma_f32_16x16x32_bf16 v[18:21], v[176:179], v[204:207], v[18:21]
	v_mfma_f32_16x16x32_bf16 v[6:9], v[168:171], v[212:215], v[6:9]
	v_mfma_f32_16x16x32_bf16 v[2:5], v[176:179], v[212:215], v[2:5]
	v_mfma_f32_16x16x32_bf16 v[54:57], v[172:175], v[188:191], v[54:57]
	v_mfma_f32_16x16x32_bf16 v[50:53], v[180:183], v[188:191], v[50:53]
	v_mfma_f32_16x16x32_bf16 v[38:41], v[172:175], v[200:203], v[38:41]
	v_mfma_f32_16x16x32_bf16 v[34:37], v[180:183], v[200:203], v[34:37]
	v_mfma_f32_16x16x32_bf16 v[22:25], v[172:175], v[208:211], v[22:25]
	v_mfma_f32_16x16x32_bf16 v[18:21], v[180:183], v[208:211], v[18:21]
	v_mfma_f32_16x16x32_bf16 v[6:9], v[172:175], v[216:219], v[6:9]
	v_mfma_f32_16x16x32_bf16 v[2:5], v[180:183], v[216:219], v[2:5]
	s_barrier
	s_add_i32 s55, s55, 2
	s_add_u32 s53, s53, 0x100
	s_addc_u32 s54, s54, 0
	s_add_u32 s30, s30, 0x100
	s_addc_u32 s31, s31, 0
	s_cmp_gt_u32 s55, 29
	s_cbranch_scc0 .LBB0_808
	s_and_b64 vcc, exec, s[12:13]
	s_cbranch_vccz .LBB0_811
	s_barrier

.LBB0_1031:
	ds_read_b128 v[144:147], v139
	ds_read_b128 v[148:151], v139 offset:1024
	ds_read_b128 v[152:155], v139 offset:2048
	ds_read_b128 v[156:159], v139 offset:3072
	ds_read_b128 v[164:167], v140
	ds_read_b128 v[168:171], v140 offset:1024
	ds_read_b128 v[172:175], v140 offset:2048
	ds_read_b128 v[176:179], v140 offset:3072
	s_add_u32 s12, s8, s10
	s_addc_u32 s13, s9, s11
	s_add_u32 s12, s12, 0x2000100
	s_addc_u32 s13, s13, 0
	s_add_u32 s42, s27, s10
	s_addc_u32 s43, s28, s11
	s_cmpk_eq_i32 s10, 0x3f00
	s_cselect_b32 s15, s3, s13
	s_cselect_b32 s14, s2, s12
	s_cselect_b32 s13, s1, s43
	s_cselect_b32 s12, s0, s42
	s_mov_b32 m0, s30
	v_lshl_add_u64 v[160:161], v[134:135], 0, s[10:11]
	ds_read_b128 v[180:183], v141
	ds_read_b128 v[184:187], v141 offset:1024
	ds_read_b128 v[188:191], v141 offset:2048
	ds_read_b128 v[196:199], v141 offset:3072
	ds_read_b128 v[200:203], v141 offset:4096
	ds_read_b128 v[204:207], v141 offset:5120
	ds_read_b128 v[208:211], v141 offset:6144
	ds_read_b128 v[212:215], v141 offset:7168
	global_load_lds_dwordx4 v[160:161], off
	v_lshl_add_u64 v[160:161], v[136:137], 0, s[10:11]
	s_mov_b32 m0, s31
	s_nop 0
	global_load_lds_dwordx4 v[160:161], off
	s_waitcnt vmcnt(8) lgkmcnt(0)
	s_barrier
	v_mfma_f32_16x16x32_bf16 v[126:129], v[144:147], v[180:183], v[126:129]
	v_mfma_f32_16x16x32_bf16 v[122:125], v[152:155], v[180:183], v[122:125]
	v_mfma_f32_16x16x32_bf16 v[110:113], v[144:147], v[188:191], v[110:113]
	v_mfma_f32_16x16x32_bf16 v[106:109], v[152:155], v[188:191], v[106:109]
	v_mfma_f32_16x16x32_bf16 v[94:97], v[144:147], v[200:203], v[94:97]
	v_mfma_f32_16x16x32_bf16 v[90:93], v[152:155], v[200:203], v[90:93]
	v_mfma_f32_16x16x32_bf16 v[78:81], v[144:147], v[208:211], v[78:81]
	v_mfma_f32_16x16x32_bf16 v[74:77], v[152:155], v[208:211], v[74:77]
	v_mfma_f32_16x16x32_bf16 v[126:129], v[148:151], v[184:187], v[126:129]
	v_mfma_f32_16x16x32_bf16 v[122:125], v[156:159], v[184:187], v[122:125]
	v_mfma_f32_16x16x32_bf16 v[110:113], v[148:151], v[196:199], v[110:113]
	v_mfma_f32_16x16x32_bf16 v[106:109], v[156:159], v[196:199], v[106:109]
	v_mfma_f32_16x16x32_bf16 v[94:97], v[148:151], v[204:207], v[94:97]
	v_mfma_f32_16x16x32_bf16 v[90:93], v[156:159], v[204:207], v[90:93]
	v_mfma_f32_16x16x32_bf16 v[78:81], v[148:151], v[212:215], v[78:81]
	v_mfma_f32_16x16x32_bf16 v[74:77], v[156:159], v[212:215], v[74:77]
	v_mfma_f32_16x16x32_bf16 v[118:121], v[164:167], v[180:183], v[118:121]
	v_mfma_f32_16x16x32_bf16 v[114:117], v[172:175], v[180:183], v[114:117]
	v_mfma_f32_16x16x32_bf16 v[102:105], v[164:167], v[188:191], v[102:105]
	v_mfma_f32_16x16x32_bf16 v[98:101], v[172:175], v[188:191], v[98:101]
	v_mfma_f32_16x16x32_bf16 v[86:89], v[164:167], v[200:203], v[86:89]
	v_mfma_f32_16x16x32_bf16 v[82:85], v[172:175], v[200:203], v[82:85]
	v_mfma_f32_16x16x32_bf16 v[70:73], v[164:167], v[208:211], v[70:73]
	v_mfma_f32_16x16x32_bf16 v[66:69], v[172:175], v[208:211], v[66:69]
	v_mfma_f32_16x16x32_bf16 v[118:121], v[168:171], v[184:187], v[118:121]
	v_mfma_f32_16x16x32_bf16 v[114:117], v[176:179], v[184:187], v[114:117]
	v_mfma_f32_16x16x32_bf16 v[102:105], v[168:171], v[196:199], v[102:105]
	v_mfma_f32_16x16x32_bf16 v[98:101], v[176:179], v[196:199], v[98:101]
	v_mfma_f32_16x16x32_bf16 v[86:89], v[168:171], v[204:207], v[86:89]
	v_mfma_f32_16x16x32_bf16 v[82:85], v[176:179], v[204:207], v[82:85]
	v_mfma_f32_16x16x32_bf16 v[70:73], v[168:171], v[212:215], v[70:73]
	v_mfma_f32_16x16x32_bf16 v[66:69], v[176:179], v[212:215], v[66:69]
	s_barrier
	s_mov_b32 m0, s34
	s_add_u32 s42, s12, 0x200000
	s_addc_u32 s43, s13, 0
	ds_read_b128 v[180:183], v141 offset:16384
	ds_read_b128 v[184:187], v141 offset:17408
	ds_read_b128 v[188:191], v141 offset:18432
	ds_read_b128 v[196:199], v141 offset:19456
	ds_read_b128 v[200:203], v141 offset:20480
	ds_read_b128 v[204:207], v141 offset:21504
	ds_read_b128 v[208:211], v141 offset:22528
	ds_read_b128 v[212:215], v141 offset:23552
	global_load_lds_dwordx4 v130, s[12:13]
	s_mov_b32 m0, s35
	s_nop 0
	global_load_lds_dwordx4 v132, s[12:13]
	s_mov_b32 m0, s36
	s_nop 0
	global_load_lds_dwordx4 v130, s[42:43]
	s_mov_b32 m0, s37
	s_nop 0
	global_load_lds_dwordx4 v132, s[42:43]
	s_mov_b32 m0, s20
	s_nop 0
	global_load_lds_dwordx4 v130, s[14:15]
	s_mov_b32 m0, s21
	s_nop 0
	global_load_lds_dwordx4 v132, s[14:15]
	s_waitcnt vmcnt(8) lgkmcnt(0)
	s_barrier
	v_mfma_f32_16x16x32_bf16 v[62:65], v[144:147], v[180:183], v[62:65]
	v_mfma_f32_16x16x32_bf16 v[58:61], v[152:155], v[180:183], v[58:61]
	v_mfma_f32_16x16x32_bf16 v[46:49], v[144:147], v[188:191], v[46:49]
	v_mfma_f32_16x16x32_bf16 v[42:45], v[152:155], v[188:191], v[42:45]
	v_mfma_f32_16x16x32_bf16 v[30:33], v[144:147], v[200:203], v[30:33]
	v_mfma_f32_16x16x32_bf16 v[26:29], v[152:155], v[200:203], v[26:29]
	v_mfma_f32_16x16x32_bf16 v[14:17], v[144:147], v[208:211], v[14:17]
	v_mfma_f32_16x16x32_bf16 v[10:13], v[152:155], v[208:211], v[10:13]
	v_mfma_f32_16x16x32_bf16 v[62:65], v[148:151], v[184:187], v[62:65]
	v_mfma_f32_16x16x32_bf16 v[58:61], v[156:159], v[184:187], v[58:61]
	v_mfma_f32_16x16x32_bf16 v[46:49], v[148:151], v[196:199], v[46:49]
	v_mfma_f32_16x16x32_bf16 v[42:45], v[156:159], v[196:199], v[42:45]
	v_mfma_f32_16x16x32_bf16 v[30:33], v[148:151], v[204:207], v[30:33]
	v_mfma_f32_16x16x32_bf16 v[26:29], v[156:159], v[204:207], v[26:29]
	v_mfma_f32_16x16x32_bf16 v[14:17], v[148:151], v[212:215], v[14:17]
	v_mfma_f32_16x16x32_bf16 v[10:13], v[156:159], v[212:215], v[10:13]
	v_mfma_f32_16x16x32_bf16 v[54:57], v[164:167], v[180:183], v[54:57]
	v_mfma_f32_16x16x32_bf16 v[50:53], v[172:175], v[180:183], v[50:53]
	v_mfma_f32_16x16x32_bf16 v[38:41], v[164:167], v[188:191], v[38:41]
	v_mfma_f32_16x16x32_bf16 v[34:37], v[172:175], v[188:191], v[34:37]
	v_mfma_f32_16x16x32_bf16 v[22:25], v[164:167], v[200:203], v[22:25]
	v_mfma_f32_16x16x32_bf16 v[18:21], v[172:175], v[200:203], v[18:21]
	v_mfma_f32_16x16x32_bf16 v[6:9], v[164:167], v[208:211], v[6:9]
	v_mfma_f32_16x16x32_bf16 v[2:5], v[172:175], v[208:211], v[2:5]
	v_mfma_f32_16x16x32_bf16 v[54:57], v[168:171], v[184:187], v[54:57]
	v_mfma_f32_16x16x32_bf16 v[50:53], v[176:179], v[184:187], v[50:53]
	v_mfma_f32_16x16x32_bf16 v[38:41], v[168:171], v[196:199], v[38:41]
	v_mfma_f32_16x16x32_bf16 v[34:37], v[176:179], v[196:199], v[34:37]
	v_mfma_f32_16x16x32_bf16 v[22:25], v[168:171], v[204:207], v[22:25]
	v_mfma_f32_16x16x32_bf16 v[18:21], v[176:179], v[204:207], v[18:21]
	v_mfma_f32_16x16x32_bf16 v[6:9], v[168:171], v[212:215], v[6:9]
	v_mfma_f32_16x16x32_bf16 v[2:5], v[176:179], v[212:215], v[2:5]
	s_barrier
	ds_read_b128 v[144:147], v142
	ds_read_b128 v[148:151], v142 offset:1024
	ds_read_b128 v[152:155], v142 offset:2048
	ds_read_b128 v[156:159], v142 offset:3072
	ds_read_b128 v[164:167], v143
	ds_read_b128 v[168:171], v143 offset:1024
	ds_read_b128 v[172:175], v143 offset:2048
	ds_read_b128 v[176:179], v143 offset:3072
	s_add_u32 s14, s14, 0x200000
	s_addc_u32 s15, s15, 0
	s_mov_b32 m0, s22
	ds_read_b128 v[180:183], v141 offset:32768
	ds_read_b128 v[184:187], v141 offset:33792
	ds_read_b128 v[188:191], v141 offset:34816
	ds_read_b128 v[196:199], v141 offset:35840
	ds_read_b128 v[200:203], v141 offset:36864
	ds_read_b128 v[204:207], v141 offset:37888
	ds_read_b128 v[208:211], v141 offset:38912
	ds_read_b128 v[212:215], v141 offset:39936
	global_load_lds_dwordx4 v130, s[14:15]
	s_mov_b32 m0, s23
	s_nop 0
	global_load_lds_dwordx4 v132, s[14:15]
	s_waitcnt vmcnt(8) lgkmcnt(0)
	s_barrier
	v_mfma_f32_16x16x32_bf16 v[126:129], v[144:147], v[180:183], v[126:129]
	v_mfma_f32_16x16x32_bf16 v[122:125], v[152:155], v[180:183], v[122:125]
	v_mfma_f32_16x16x32_bf16 v[110:113], v[144:147], v[188:191], v[110:113]
	v_mfma_f32_16x16x32_bf16 v[106:109], v[152:155], v[188:191], v[106:109]
	v_mfma_f32_16x16x32_bf16 v[94:97], v[144:147], v[200:203], v[94:97]
	v_mfma_f32_16x16x32_bf16 v[90:93], v[152:155], v[200:203], v[90:93]
	v_mfma_f32_16x16x32_bf16 v[78:81], v[144:147], v[208:211], v[78:81]
	v_mfma_f32_16x16x32_bf16 v[74:77], v[152:155], v[208:211], v[74:77]
	v_mfma_f32_16x16x32_bf16 v[126:129], v[148:151], v[184:187], v[126:129]
	v_mfma_f32_16x16x32_bf16 v[122:125], v[156:159], v[184:187], v[122:125]
	v_mfma_f32_16x16x32_bf16 v[110:113], v[148:151], v[196:199], v[110:113]
	v_mfma_f32_16x16x32_bf16 v[106:109], v[156:159], v[196:199], v[106:109]
	v_mfma_f32_16x16x32_bf16 v[94:97], v[148:151], v[204:207], v[94:97]
	v_mfma_f32_16x16x32_bf16 v[90:93], v[156:159], v[204:207], v[90:93]
	v_mfma_f32_16x16x32_bf16 v[78:81], v[148:151], v[212:215], v[78:81]
	v_mfma_f32_16x16x32_bf16 v[74:77], v[156:159], v[212:215], v[74:77]
	v_mfma_f32_16x16x32_bf16 v[118:121], v[164:167], v[180:183], v[118:121]
	v_mfma_f32_16x16x32_bf16 v[114:117], v[172:175], v[180:183], v[114:117]
	v_mfma_f32_16x16x32_bf16 v[102:105], v[164:167], v[188:191], v[102:105]
	v_mfma_f32_16x16x32_bf16 v[98:101], v[172:175], v[188:191], v[98:101]
	v_mfma_f32_16x16x32_bf16 v[86:89], v[164:167], v[200:203], v[86:89]
	v_mfma_f32_16x16x32_bf16 v[82:85], v[172:175], v[200:203], v[82:85]
	v_mfma_f32_16x16x32_bf16 v[70:73], v[164:167], v[208:211], v[70:73]
	v_mfma_f32_16x16x32_bf16 v[66:69], v[172:175], v[208:211], v[66:69]
	v_mfma_f32_16x16x32_bf16 v[118:121], v[168:171], v[184:187], v[118:121]
	v_mfma_f32_16x16x32_bf16 v[114:117], v[176:179], v[184:187], v[114:117]
	v_mfma_f32_16x16x32_bf16 v[102:105], v[168:171], v[196:199], v[102:105]
	v_mfma_f32_16x16x32_bf16 v[98:101], v[176:179], v[196:199], v[98:101]
	v_mfma_f32_16x16x32_bf16 v[86:89], v[168:171], v[204:207], v[86:89]
	v_mfma_f32_16x16x32_bf16 v[82:85], v[176:179], v[204:207], v[82:85]
	v_mfma_f32_16x16x32_bf16 v[70:73], v[168:171], v[212:215], v[70:73]
	v_mfma_f32_16x16x32_bf16 v[66:69], v[176:179], v[212:215], v[66:69]
	s_barrier
	s_mov_b32 m0, s38
	s_add_u32 s12, s12, 0x200080
	s_addc_u32 s13, s13, 0
	ds_read_b128 v[180:183], v141 offset:49152
	ds_read_b128 v[184:187], v141 offset:50176
	ds_read_b128 v[188:191], v141 offset:51200
	ds_read_b128 v[196:199], v141 offset:52224
	ds_read_b128 v[200:203], v141 offset:53248
	ds_read_b128 v[204:207], v141 offset:54272
	ds_read_b128 v[208:211], v141 offset:55296
	ds_read_b128 v[212:215], v141 offset:56320
	s_add_u32 s98, s12, 0xffe00000
	s_addc_u32 s99, s13, -1
	global_load_lds_dwordx4 v130, s[98:99]
	s_mov_b32 m0, s39
	s_nop 0
	global_load_lds_dwordx4 v132, s[98:99]
	s_mov_b32 m0, s40
	s_nop 0
	global_load_lds_dwordx4 v130, s[12:13]
	s_mov_b32 m0, s41
	s_nop 0
	global_load_lds_dwordx4 v132, s[12:13]
	s_mov_b32 m0, s25
	s_nop 0
	s_add_u32 s100, s14, 0xffe00080
	s_addc_u32 s101, s15, -1
	global_load_lds_dwordx4 v130, s[100:101]
	s_mov_b32 m0, s26
	s_nop 0
	global_load_lds_dwordx4 v132, s[100:101]
	s_waitcnt vmcnt(8) lgkmcnt(0)
	s_barrier
	v_mfma_f32_16x16x32_bf16 v[62:65], v[144:147], v[180:183], v[62:65]
	v_mfma_f32_16x16x32_bf16 v[58:61], v[152:155], v[180:183], v[58:61]
	v_mfma_f32_16x16x32_bf16 v[46:49], v[144:147], v[188:191], v[46:49]
	v_mfma_f32_16x16x32_bf16 v[42:45], v[152:155], v[188:191], v[42:45]
	v_mfma_f32_16x16x32_bf16 v[30:33], v[144:147], v[200:203], v[30:33]
	v_mfma_f32_16x16x32_bf16 v[26:29], v[152:155], v[200:203], v[26:29]
	v_mfma_f32_16x16x32_bf16 v[14:17], v[144:147], v[208:211], v[14:17]
	v_mfma_f32_16x16x32_bf16 v[10:13], v[152:155], v[208:211], v[10:13]
	v_mfma_f32_16x16x32_bf16 v[62:65], v[148:151], v[184:187], v[62:65]
	v_mfma_f32_16x16x32_bf16 v[58:61], v[156:159], v[184:187], v[58:61]
	v_mfma_f32_16x16x32_bf16 v[46:49], v[148:151], v[196:199], v[46:49]
	v_mfma_f32_16x16x32_bf16 v[42:45], v[156:159], v[196:199], v[42:45]
	v_mfma_f32_16x16x32_bf16 v[30:33], v[148:151], v[204:207], v[30:33]
	v_mfma_f32_16x16x32_bf16 v[26:29], v[156:159], v[204:207], v[26:29]
	v_mfma_f32_16x16x32_bf16 v[14:17], v[148:151], v[212:215], v[14:17]
	v_mfma_f32_16x16x32_bf16 v[10:13], v[156:159], v[212:215], v[10:13]
	v_mfma_f32_16x16x32_bf16 v[54:57], v[164:167], v[180:183], v[54:57]
	v_mfma_f32_16x16x32_bf16 v[50:53], v[172:175], v[180:183], v[50:53]
	v_mfma_f32_16x16x32_bf16 v[38:41], v[164:167], v[188:191], v[38:41]
	v_mfma_f32_16x16x32_bf16 v[34:37], v[172:175], v[188:191], v[34:37]
	v_mfma_f32_16x16x32_bf16 v[22:25], v[164:167], v[200:203], v[22:25]
	v_mfma_f32_16x16x32_bf16 v[18:21], v[172:175], v[200:203], v[18:21]
	v_mfma_f32_16x16x32_bf16 v[6:9], v[164:167], v[208:211], v[6:9]
	v_mfma_f32_16x16x32_bf16 v[2:5], v[172:175], v[208:211], v[2:5]
	v_mfma_f32_16x16x32_bf16 v[54:57], v[168:171], v[184:187], v[54:57]
	v_mfma_f32_16x16x32_bf16 v[50:53], v[176:179], v[184:187], v[50:53]
	v_mfma_f32_16x16x32_bf16 v[38:41], v[168:171], v[196:199], v[38:41]
	v_mfma_f32_16x16x32_bf16 v[34:37], v[176:179], v[196:199], v[34:37]
	v_mfma_f32_16x16x32_bf16 v[22:25], v[168:171], v[204:207], v[22:25]
	v_mfma_f32_16x16x32_bf16 v[18:21], v[176:179], v[204:207], v[18:21]
	v_mfma_f32_16x16x32_bf16 v[6:9], v[168:171], v[212:215], v[6:9]
	v_mfma_f32_16x16x32_bf16 v[2:5], v[176:179], v[212:215], v[2:5]
	s_barrier
	s_add_i32 s29, s29, 2
	s_add_u32 s10, s10, 0x100
	s_addc_u32 s11, s11, 0
	s_cmpk_lt_u32 s29, 0x7e
	s_cbranch_scc1 .LBB0_1031
	s_waitcnt vmcnt(0)
	s_cmpk_gt_u32 s19, 0xff
	s_cbranch_scc1 .LBB0_1034
	s_barrier
